# prep z_b park copy: all 16 row loads in flight per thread instead of 4 rolling
# speedup vs baseline: 1.0024x; 1.0024x over previous
.LBB0_704:
	s_nop 0
	v_add_co_u32_e32 v0, vcc, 0xfd600000, v88
	s_mov_b32 s3, 0xfe400000
	s_nop 0
	v_addc_co_u32_e32 v1, vcc, -1, v89, vcc
	global_load_dwordx4 v[96:99], v[0:1], off offset:-64
	global_load_dwordx4 v[100:103], v[0:1], off
	global_load_dwordx4 v[30:33], v[80:81], off offset:48
	global_load_dwordx4 v[42:45], v[80:81], off offset:32
	global_load_dwordx4 v[46:49], v[80:81], off offset:16
	global_load_dwordx4 v[50:53], v[80:81], off
	v_add_co_u32_e32 v0, vcc, s3, v88
	s_mov_b32 s3, 0xff200000
	s_nop 0
	v_addc_co_u32_e32 v1, vcc, -1, v89, vcc
	global_load_dwordx4 v[54:57], v[0:1], off offset:-64
	global_load_dwordx4 v[58:61], v[0:1], off
	v_add_u32_e32 v0, 0xffff0000, v92
	v_and_or_b32 v0, v0, s8, v78
	v_lshlrev_b32_e32 v0, 3, v0
	global_load_dwordx4 v[62:65], v0, s[0:1] offset:48
	global_load_dwordx4 v[66:69], v0, s[0:1] offset:32
	global_load_dwordx4 v[70:73], v0, s[0:1] offset:16
	global_load_dwordx4 v[74:77], v0, s[0:1]
	v_add_co_u32_e32 v0, vcc, s3, v88
	v_and_or_b32 v4, v92, s8, v78
	s_nop 0
	v_addc_co_u32_e32 v1, vcc, -1, v89, vcc
	v_lshlrev_b32_e32 v26, 3, v4
	global_load_dwordx4 v[34:37], v[0:1], off offset:-64
	global_load_dwordx4 v[38:41], v[0:1], off
	s_nop 0
	global_load_dwordx4 v[0:3], v[88:89], off offset:-64
	global_load_dwordx4 v[14:17], v[88:89], off
	global_load_dwordx4 v[4:7], v26, s[0:1] offset:48
	global_load_dwordx4 v[18:21], v26, s[0:1] offset:32
	global_load_dwordx4 v[22:25], v26, s[0:1] offset:16
	s_nop 0
	global_load_dwordx4 v[26:29], v26, s[0:1]
	v_add_u32_e32 v108, 0x400, v93
	v_add_u32_e32 v95, 0x800, v93
	v_add_u32_e32 v94, 0xc00, v93
	s_waitcnt vmcnt(18)
	v_lshlrev_b32_e32 v105, 16, v100
	v_lshlrev_b32_e32 v104, 16, v96
	s_waitcnt vmcnt(14)
	v_pk_mul_f32 v[106:107], v[50:51], v[104:105]
	v_pk_mul_f32 v[104:105], v[50:51], v[104:105] op_sel:[1,0] op_sel_hi:[0,1]
	v_add_f32_e32 v110, v104, v105
	v_and_b32_e32 v105, 0xffff0000, v100
	v_and_b32_e32 v104, 0xffff0000, v96
	v_sub_f32_e32 v109, v106, v107
	v_pk_mul_f32 v[106:107], v[52:53], v[104:105]
	v_pk_mul_f32 v[104:105], v[52:53], v[104:105] op_sel:[1,0] op_sel_hi:[0,1]
	v_add_f32_e32 v112, v104, v105
	v_lshlrev_b32_e32 v105, 16, v101
	v_lshlrev_b32_e32 v104, 16, v97
	v_and_b32_e32 v101, 0xffff0000, v101
	v_and_b32_e32 v100, 0xffff0000, v97
	v_sub_f32_e32 v111, v106, v107
	v_pk_mul_f32 v[106:107], v[46:47], v[104:105]
	v_pk_mul_f32 v[104:105], v[46:47], v[104:105] op_sel:[0,1] op_sel_hi:[1,0]
	v_pk_mul_f32 v[96:97], v[48:49], v[100:101]
	v_add_f32_e32 v104, v104, v105
	v_sub_f32_e32 v105, v96, v97
	v_pk_mul_f32 v[96:97], v[48:49], v[100:101] op_sel:[1,0] op_sel_hi:[0,1]
	v_sub_f32_e32 v106, v106, v107
	v_add_f32_e32 v107, v96, v97
	v_lshlrev_b32_e32 v97, 16, v102
	v_lshlrev_b32_e32 v96, 16, v98
	v_pk_mul_f32 v[100:101], v[42:43], v[96:97]
	v_pk_mul_f32 v[96:97], v[42:43], v[96:97] op_sel:[0,1] op_sel_hi:[1,0]
	v_sub_f32_e32 v113, v100, v101
	v_add_f32_e32 v114, v96, v97
	v_and_b32_e32 v97, 0xffff0000, v102
	v_and_b32_e32 v96, 0xffff0000, v98
	v_pk_mul_f32 v[100:101], v[44:45], v[96:97]
	v_pk_mul_f32 v[96:97], v[44:45], v[96:97] op_sel:[1,0] op_sel_hi:[0,1]
	v_add_f32_e32 v115, v96, v97
	v_lshlrev_b32_e32 v97, 16, v103
	v_lshlrev_b32_e32 v96, 16, v99
	v_sub_f32_e32 v102, v100, v101
	v_pk_mul_f32 v[100:101], v[30:31], v[96:97]
	v_pk_mul_f32 v[96:97], v[30:31], v[96:97] op_sel:[0,1] op_sel_hi:[1,0]
	v_sub_f32_e32 v116, v100, v101
	v_add_f32_e32 v117, v96, v97
	v_and_b32_e32 v97, 0xffff0000, v103
	v_and_b32_e32 v96, 0xffff0000, v99
	v_pk_mul_f32 v[98:99], v[32:33], v[96:97]
	v_pk_mul_f32 v[96:97], v[32:33], v[96:97] op_sel:[1,0] op_sel_hi:[0,1]
	v_add_f32_e32 v103, v96, v97
	v_ashrrev_i32_e32 v96, 11, v93
	v_mad_i32_i24 v96, v96, 24, v79
	v_ashrrev_i32_e32 v97, 31, v96
	v_lshlrev_b64 v[96:97], 18, v[96:97]
	v_sub_f32_e32 v99, v98, v99
	v_lshl_add_u64 v[100:101], v[84:85], 0, v[96:97]
	v_cvt_pk_bf16_f32 v96, v109, v111
	v_cvt_pk_bf16_f32 v97, v106, v105
	v_cvt_pk_bf16_f32 v98, v113, v102
	v_cvt_pk_bf16_f32 v99, v116, v99
	global_store_dwordx4 v[100:101], v[96:99], off
	s_add_i32 s2, s2, 4
	s_mov_b64 s[6:7], 0x3800000
	v_cvt_pk_bf16_f32 v96, v110, v112
	v_cvt_pk_bf16_f32 v97, v104, v107
	v_cvt_pk_bf16_f32 v98, v114, v115
	v_cvt_pk_bf16_f32 v99, v117, v103
	global_store_dwordx4 v[100:101], v[96:99], off offset:64
	v_add_u32_e32 v93, 0x1000, v93
	v_add_u32_e32 v92, 0x20000, v92
	s_waitcnt vmcnt(14)
	v_lshlrev_b32_e32 v97, 16, v58
	v_lshlrev_b32_e32 v96, 16, v54
	s_waitcnt vmcnt(10)
	v_pk_mul_f32 v[98:99], v[74:75], v[96:97]
	v_pk_mul_f32 v[74:75], v[74:75], v[96:97] op_sel:[1,0] op_sel_hi:[0,1]
	v_sub_f32_e32 v98, v98, v99
	v_add_f32_e32 v99, v74, v75
	v_and_b32_e32 v75, 0xffff0000, v58
	v_and_b32_e32 v74, 0xffff0000, v54
	v_pk_mul_f32 v[96:97], v[76:77], v[74:75]
	v_pk_mul_f32 v[74:75], v[76:77], v[74:75] op_sel:[1,0] op_sel_hi:[0,1]
	v_sub_f32_e32 v96, v96, v97
	v_add_f32_e32 v97, v74, v75
	v_lshlrev_b32_e32 v75, 16, v59
	v_lshlrev_b32_e32 v74, 16, v55
	v_and_b32_e32 v59, 0xffff0000, v59
	v_and_b32_e32 v58, 0xffff0000, v55
	v_pk_mul_f32 v[76:77], v[70:71], v[74:75]
	v_pk_mul_f32 v[70:71], v[70:71], v[74:75] op_sel:[0,1] op_sel_hi:[1,0]
	v_pk_mul_f32 v[54:55], v[72:73], v[58:59]
	v_add_f32_e32 v70, v70, v71
	v_sub_f32_e32 v71, v54, v55
	v_pk_mul_f32 v[54:55], v[72:73], v[58:59] op_sel:[1,0] op_sel_hi:[0,1]
	v_add_f32_e32 v72, v54, v55
	v_lshlrev_b32_e32 v55, 16, v60
	v_lshlrev_b32_e32 v54, 16, v56
	v_pk_mul_f32 v[58:59], v[66:67], v[54:55]
	v_pk_mul_f32 v[54:55], v[66:67], v[54:55] op_sel:[0,1] op_sel_hi:[1,0]
	v_sub_f32_e32 v73, v58, v59
	v_add_f32_e32 v66, v54, v55
	v_and_b32_e32 v55, 0xffff0000, v60
	v_and_b32_e32 v54, 0xffff0000, v56
	v_pk_mul_f32 v[58:59], v[68:69], v[54:55]
	v_pk_mul_f32 v[54:55], v[68:69], v[54:55] op_sel:[1,0] op_sel_hi:[0,1]
	v_add_f32_e32 v67, v54, v55
	v_lshlrev_b32_e32 v55, 16, v61
	v_lshlrev_b32_e32 v54, 16, v57
	v_sub_f32_e32 v60, v58, v59
	v_pk_mul_f32 v[58:59], v[62:63], v[54:55]
	v_pk_mul_f32 v[54:55], v[62:63], v[54:55] op_sel:[0,1] op_sel_hi:[1,0]
	v_sub_f32_e32 v76, v76, v77
	v_add_f32_e32 v62, v54, v55
	v_and_b32_e32 v55, 0xffff0000, v61
	v_and_b32_e32 v54, 0xffff0000, v57
	v_pk_mul_f32 v[56:57], v[64:65], v[54:55]
	v_pk_mul_f32 v[54:55], v[64:65], v[54:55] op_sel:[1,0] op_sel_hi:[0,1]
	v_add_f32_e32 v61, v54, v55
	v_ashrrev_i32_e32 v54, 11, v108
	v_lshlrev_b32_e32 v55, v90, v108
	v_mad_i32_i24 v54, v54, 24, v79
	v_sub_f32_e32 v57, v56, v57
	v_and_b32_e32 v56, 0x7fe, v55
	v_ashrrev_i32_e32 v55, 31, v54
	v_lshlrev_b64 v[54:55], 18, v[54:55]
	v_lshl_add_u64 v[54:55], s[4:5], 0, v[54:55]
	v_add_lshl_u32 v194, v56, v91, 7
	v_lshl_add_u64 v[54:55], v[54:55], 0, v[194:195]
	v_lshlrev_b32_e32 v194, 1, v78
	v_sub_f32_e32 v68, v58, v59
	v_lshl_add_u64 v[58:59], v[54:55], 0, v[194:195]
	v_cvt_pk_bf16_f32 v54, v98, v96
	v_cvt_pk_bf16_f32 v55, v76, v71
	v_cvt_pk_bf16_f32 v56, v73, v60
	v_cvt_pk_bf16_f32 v57, v68, v57
	global_store_dwordx4 v[58:59], v[54:57], off
	v_lshl_add_u64 v[88:89], v[88:89], 0, s[6:7]
	s_cmp_lt_u32 s2, 12
	v_cvt_pk_bf16_f32 v54, v99, v97
	v_cvt_pk_bf16_f32 v55, v70, v72
	v_cvt_pk_bf16_f32 v56, v66, v67
	v_cvt_pk_bf16_f32 v57, v62, v61
	global_store_dwordx4 v[58:59], v[54:57], off offset:64
	s_waitcnt vmcnt(10)
	s_nop 0
	v_lshlrev_b32_e32 v55, 16, v38
	v_lshlrev_b32_e32 v54, 16, v34
	v_pk_mul_f32 v[56:57], v[50:51], v[54:55]
	v_pk_mul_f32 v[50:51], v[50:51], v[54:55] op_sel:[1,0] op_sel_hi:[0,1]
	v_sub_f32_e32 v56, v56, v57
	v_add_f32_e32 v57, v50, v51
	v_and_b32_e32 v51, 0xffff0000, v38
	v_and_b32_e32 v50, 0xffff0000, v34
	v_pk_mul_f32 v[54:55], v[52:53], v[50:51]
	v_pk_mul_f32 v[50:51], v[52:53], v[50:51] op_sel:[1,0] op_sel_hi:[0,1]
	v_sub_f32_e32 v54, v54, v55
	v_add_f32_e32 v55, v50, v51
	v_lshlrev_b32_e32 v51, 16, v39
	v_lshlrev_b32_e32 v50, 16, v35
	v_and_b32_e32 v39, 0xffff0000, v39
	v_and_b32_e32 v38, 0xffff0000, v35
	v_pk_mul_f32 v[52:53], v[46:47], v[50:51]
	v_pk_mul_f32 v[46:47], v[46:47], v[50:51] op_sel:[1,0] op_sel_hi:[0,1]
	v_pk_mul_f32 v[34:35], v[48:49], v[38:39]
	v_add_f32_e32 v46, v46, v47
	v_sub_f32_e32 v47, v34, v35
	v_pk_mul_f32 v[34:35], v[48:49], v[38:39] op_sel:[1,0] op_sel_hi:[0,1]
	v_add_f32_e32 v48, v34, v35
	v_lshlrev_b32_e32 v35, 16, v40
	v_lshlrev_b32_e32 v34, 16, v36
	v_pk_mul_f32 v[38:39], v[42:43], v[34:35]
	v_pk_mul_f32 v[34:35], v[42:43], v[34:35] op_sel:[1,0] op_sel_hi:[0,1]
	v_add_f32_e32 v42, v34, v35
	v_and_b32_e32 v35, 0xffff0000, v40
	v_and_b32_e32 v34, 0xffff0000, v36
	v_sub_f32_e32 v49, v38, v39
	v_pk_mul_f32 v[38:39], v[44:45], v[34:35]
	v_pk_mul_f32 v[34:35], v[44:45], v[34:35] op_sel:[1,0] op_sel_hi:[0,1]
	v_add_f32_e32 v40, v34, v35
	v_lshlrev_b32_e32 v35, 16, v41
	v_lshlrev_b32_e32 v34, 16, v37
	v_sub_f32_e32 v36, v38, v39
	v_pk_mul_f32 v[38:39], v[30:31], v[34:35]
	v_pk_mul_f32 v[30:31], v[30:31], v[34:35] op_sel:[1,0] op_sel_hi:[0,1]
	v_sub_f32_e32 v38, v38, v39
	v_add_f32_e32 v39, v30, v31
	v_and_b32_e32 v31, 0xffff0000, v41
	v_and_b32_e32 v30, 0xffff0000, v37
	v_pk_mul_f32 v[34:35], v[32:33], v[30:31]
	v_pk_mul_f32 v[30:31], v[32:33], v[30:31] op_sel:[1,0] op_sel_hi:[0,1]
	v_add_f32_e32 v41, v30, v31
	v_ashrrev_i32_e32 v30, 11, v95
	v_mad_i32_i24 v30, v30, 24, v79
	v_ashrrev_i32_e32 v31, 31, v30
	v_lshlrev_b64 v[30:31], 18, v[30:31]
	v_sub_f32_e32 v52, v52, v53
	v_sub_f32_e32 v37, v34, v35
	v_lshl_add_u64 v[34:35], v[84:85], 0, v[30:31]
	v_cvt_pk_bf16_f32 v30, v56, v54
	v_cvt_pk_bf16_f32 v31, v52, v47
	v_cvt_pk_bf16_f32 v32, v49, v36
	v_cvt_pk_bf16_f32 v33, v38, v37
	global_store_dwordx4 v[34:35], v[30:33], off
	s_nop 1
	v_cvt_pk_bf16_f32 v30, v57, v55
	v_cvt_pk_bf16_f32 v31, v46, v48
	v_cvt_pk_bf16_f32 v32, v42, v40
	v_cvt_pk_bf16_f32 v33, v39, v41
	global_store_dwordx4 v[34:35], v[30:33], off offset:64
	s_waitcnt vmcnt(10)
	s_nop 0
	v_lshlrev_b32_e32 v31, 16, v14
	v_lshlrev_b32_e32 v30, 16, v0
	s_waitcnt vmcnt(6)
	v_pk_mul_f32 v[32:33], v[26:27], v[30:31]
	v_pk_mul_f32 v[26:27], v[26:27], v[30:31] op_sel:[1,0] op_sel_hi:[0,1]
	v_sub_f32_e32 v32, v32, v33
	v_add_f32_e32 v33, v26, v27
	v_and_b32_e32 v27, 0xffff0000, v14
	v_and_b32_e32 v26, 0xffff0000, v0
	v_pk_mul_f32 v[30:31], v[28:29], v[26:27]
	v_pk_mul_f32 v[26:27], v[28:29], v[26:27] op_sel:[1,0] op_sel_hi:[0,1]
	v_sub_f32_e32 v30, v30, v31
	v_add_f32_e32 v31, v26, v27
	v_lshlrev_b32_e32 v27, 16, v15
	v_lshlrev_b32_e32 v26, 16, v1
	v_and_b32_e32 v15, 0xffff0000, v15
	v_and_b32_e32 v14, 0xffff0000, v1
	v_pk_mul_f32 v[28:29], v[22:23], v[26:27]
	v_pk_mul_f32 v[22:23], v[22:23], v[26:27] op_sel:[0,1] op_sel_hi:[1,0]
	v_pk_mul_f32 v[0:1], v[24:25], v[14:15]
	v_add_f32_e32 v22, v22, v23
	v_sub_f32_e32 v23, v0, v1
	v_pk_mul_f32 v[0:1], v[24:25], v[14:15] op_sel:[1,0] op_sel_hi:[0,1]
	v_add_f32_e32 v24, v0, v1
	v_lshlrev_b32_e32 v1, 16, v16
	v_lshlrev_b32_e32 v0, 16, v2
	v_pk_mul_f32 v[14:15], v[18:19], v[0:1]
	v_pk_mul_f32 v[0:1], v[18:19], v[0:1] op_sel:[0,1] op_sel_hi:[1,0]
	v_sub_f32_e32 v25, v14, v15
	v_add_f32_e32 v18, v0, v1
	v_and_b32_e32 v1, 0xffff0000, v16
	v_and_b32_e32 v0, 0xffff0000, v2
	v_pk_mul_f32 v[14:15], v[20:21], v[0:1]
	v_pk_mul_f32 v[0:1], v[20:21], v[0:1] op_sel:[1,0] op_sel_hi:[0,1]
	v_add_f32_e32 v19, v0, v1
	v_lshlrev_b32_e32 v1, 16, v17
	v_lshlrev_b32_e32 v0, 16, v3
	v_sub_f32_e32 v16, v14, v15
	v_pk_mul_f32 v[14:15], v[4:5], v[0:1]
	v_pk_mul_f32 v[0:1], v[4:5], v[0:1] op_sel:[0,1] op_sel_hi:[1,0]
	v_sub_f32_e32 v14, v14, v15
	v_add_f32_e32 v15, v0, v1
	v_and_b32_e32 v1, 0xffff0000, v17
	v_and_b32_e32 v0, 0xffff0000, v3
	v_pk_mul_f32 v[2:3], v[6:7], v[0:1]
	v_pk_mul_f32 v[0:1], v[6:7], v[0:1] op_sel:[1,0] op_sel_hi:[0,1]
	v_add_f32_e32 v6, v0, v1
	v_ashrrev_i32_e32 v0, 11, v94
	v_lshlrev_b32_e32 v1, v90, v94
	v_mad_i32_i24 v0, v0, 24, v79
	v_sub_f32_e32 v17, v2, v3
	v_and_b32_e32 v2, 0x7fe, v1
	v_ashrrev_i32_e32 v1, 31, v0
	v_lshlrev_b64 v[0:1], 18, v[0:1]
	v_lshl_add_u64 v[0:1], s[4:5], 0, v[0:1]
	v_add_lshl_u32 v2, v2, v91, 7
	v_mov_b32_e32 v3, v195
	v_lshl_add_u64 v[0:1], v[0:1], 0, v[2:3]
	v_sub_f32_e32 v28, v28, v29
	v_lshl_add_u64 v[4:5], v[0:1], 0, v[194:195]
	v_cvt_pk_bf16_f32 v0, v32, v30
	v_cvt_pk_bf16_f32 v1, v28, v23
	v_cvt_pk_bf16_f32 v2, v25, v16
	v_cvt_pk_bf16_f32 v3, v14, v17
	global_store_dwordx4 v[4:5], v[0:3], off
	s_nop 1
	v_cvt_pk_bf16_f32 v0, v33, v31
	v_cvt_pk_bf16_f32 v1, v22, v24
	v_cvt_pk_bf16_f32 v2, v18, v19
	v_cvt_pk_bf16_f32 v3, v15, v6
	global_store_dwordx4 v[4:5], v[0:3], off offset:64
	s_cbranch_scc1 .LBB0_704
	v_lshlrev_b64 v[16:17], 1, v[86:87]
	v_lshl_add_u64 v[0:1], s[38:39], 0, v[16:17]
	s_mov_b64 s[0:1], 0x259eb400
	v_lshl_add_u64 v[14:15], v[0:1], 0, s[0:1]
	v_lshlrev_b64 v[34:35], 12, v[8:9]
	v_lshl_add_u64 v[14:15], v[14:15], 0, v[34:35]
	v_lshl_add_u64 v[0:1], s[82:83], 0, v[82:83]
	v_lshl_add_u64 v[0:1], v[0:1], 0, v[16:17]
	s_mov_b64 s[0:1], 0x3200
	v_lshl_add_u64 v[0:1], v[0:1], 0, s[0:1]
	s_mov_b32 s1, 0
	global_load_dwordx4 v[100:103], v[0:1], off
	s_mov_b32 s0, 0xe00000
	v_lshl_add_u64 v[18:19], v[0:1], 0, s[0:1]
	global_load_dwordx4 v[104:107], v[18:19], off
	s_mov_b32 s0, 0x1c00000
	v_lshl_add_u64 v[18:19], v[0:1], 0, s[0:1]
	global_load_dwordx4 v[108:111], v[18:19], off
	s_mov_b32 s0, 0x2a00000
	v_lshl_add_u64 v[18:19], v[0:1], 0, s[0:1]
	global_load_dwordx4 v[112:115], v[18:19], off
	s_mov_b32 s0, 0x3800000
	v_lshl_add_u64 v[18:19], v[0:1], 0, s[0:1]
	global_load_dwordx4 v[116:119], v[18:19], off
	s_mov_b32 s0, 0x4600000
	v_lshl_add_u64 v[18:19], v[0:1], 0, s[0:1]
	global_load_dwordx4 v[120:123], v[18:19], off
	s_mov_b32 s0, 0x5400000
	v_lshl_add_u64 v[18:19], v[0:1], 0, s[0:1]
	global_load_dwordx4 v[124:127], v[18:19], off
	s_mov_b32 s0, 0x6200000
	v_lshl_add_u64 v[18:19], v[0:1], 0, s[0:1]
	global_load_dwordx4 v[128:131], v[18:19], off
	s_mov_b32 s0, 0x7000000
	v_lshl_add_u64 v[18:19], v[0:1], 0, s[0:1]
	global_load_dwordx4 v[132:135], v[18:19], off
	s_mov_b32 s0, 0x7e00000
	v_lshl_add_u64 v[18:19], v[0:1], 0, s[0:1]
	global_load_dwordx4 v[136:139], v[18:19], off
	s_mov_b32 s0, 0x8c00000
	v_lshl_add_u64 v[18:19], v[0:1], 0, s[0:1]
	global_load_dwordx4 v[140:143], v[18:19], off
	s_mov_b32 s0, 0x9a00000
	v_lshl_add_u64 v[18:19], v[0:1], 0, s[0:1]
	global_load_dwordx4 v[144:147], v[18:19], off
	s_mov_b32 s0, 0xa800000
	v_lshl_add_u64 v[18:19], v[0:1], 0, s[0:1]
	global_load_dwordx4 v[148:151], v[18:19], off
	s_mov_b32 s0, 0xb600000
	v_lshl_add_u64 v[18:19], v[0:1], 0, s[0:1]
	global_load_dwordx4 v[152:155], v[18:19], off
	s_mov_b32 s0, 0xc400000
	v_lshl_add_u64 v[18:19], v[0:1], 0, s[0:1]
	global_load_dwordx4 v[156:159], v[18:19], off
	s_mov_b32 s0, 0xd200000
	v_lshl_add_u64 v[18:19], v[0:1], 0, s[0:1]
	global_load_dwordx4 v[160:163], v[18:19], off
	s_mov_b32 s65, 0x800000
	s_mov_b64 s[66:67], 0x3fffff
	s_movk_i32 s2, 0x3000
	s_movk_i32 s3, 0x3800
	s_mov_b32 s0, 0x0
	v_lshl_add_u64 v[18:19], v[14:15], 0, s[0:1]
	s_waitcnt vmcnt(15)
	global_store_dwordx4 v[18:19], v[100:103], off
	s_mov_b32 s0, 0x400000
	v_lshl_add_u64 v[18:19], v[14:15], 0, s[0:1]
	s_waitcnt vmcnt(15)
	global_store_dwordx4 v[18:19], v[104:107], off
	s_mov_b32 s0, 0x800000
	v_lshl_add_u64 v[18:19], v[14:15], 0, s[0:1]
	s_waitcnt vmcnt(15)
	global_store_dwordx4 v[18:19], v[108:111], off
	s_mov_b32 s0, 0xc00000
	v_lshl_add_u64 v[18:19], v[14:15], 0, s[0:1]
	s_waitcnt vmcnt(15)
	global_store_dwordx4 v[18:19], v[112:115], off
	s_mov_b32 s0, 0x1000000
	v_lshl_add_u64 v[18:19], v[14:15], 0, s[0:1]
	s_waitcnt vmcnt(15)
	global_store_dwordx4 v[18:19], v[116:119], off
	s_mov_b32 s0, 0x1400000
	v_lshl_add_u64 v[18:19], v[14:15], 0, s[0:1]
	s_waitcnt vmcnt(15)
	global_store_dwordx4 v[18:19], v[120:123], off
	s_mov_b32 s0, 0x1800000
	v_lshl_add_u64 v[18:19], v[14:15], 0, s[0:1]
	s_waitcnt vmcnt(15)
	global_store_dwordx4 v[18:19], v[124:127], off
	s_mov_b32 s0, 0x1c00000
	v_lshl_add_u64 v[18:19], v[14:15], 0, s[0:1]
	s_waitcnt vmcnt(15)
	global_store_dwordx4 v[18:19], v[128:131], off
	s_mov_b32 s0, 0x2000000
	v_lshl_add_u64 v[18:19], v[14:15], 0, s[0:1]
	s_waitcnt vmcnt(15)
	global_store_dwordx4 v[18:19], v[132:135], off
	s_mov_b32 s0, 0x2400000
	v_lshl_add_u64 v[18:19], v[14:15], 0, s[0:1]
	s_waitcnt vmcnt(15)
	global_store_dwordx4 v[18:19], v[136:139], off
	s_mov_b32 s0, 0x2800000
	v_lshl_add_u64 v[18:19], v[14:15], 0, s[0:1]
	s_waitcnt vmcnt(15)
	global_store_dwordx4 v[18:19], v[140:143], off
	s_mov_b32 s0, 0x2c00000
	v_lshl_add_u64 v[18:19], v[14:15], 0, s[0:1]
	s_waitcnt vmcnt(15)
	global_store_dwordx4 v[18:19], v[144:147], off
	s_mov_b32 s0, 0x3000000
	v_lshl_add_u64 v[18:19], v[14:15], 0, s[0:1]
	s_waitcnt vmcnt(15)
	global_store_dwordx4 v[18:19], v[148:151], off
	s_mov_b32 s0, 0x3400000
	v_lshl_add_u64 v[18:19], v[14:15], 0, s[0:1]
	s_waitcnt vmcnt(15)
	global_store_dwordx4 v[18:19], v[152:155], off
	s_mov_b32 s0, 0x3800000
	v_lshl_add_u64 v[18:19], v[14:15], 0, s[0:1]
	s_waitcnt vmcnt(15)
	global_store_dwordx4 v[18:19], v[156:159], off
	s_mov_b32 s0, 0x3c00000
	v_lshl_add_u64 v[18:19], v[14:15], 0, s[0:1]
	s_waitcnt vmcnt(15)
	global_store_dwordx4 v[18:19], v[160:163], off
